# GEMM K-loops: M0 set-up for each LDS-DMA load hoisted ahead of the fragment reads / last MFMA of the column, removing the s_nop wait-state filler before all 8 loads per K-step
# speedup vs baseline: 1.0039x; 1.0039x over previous
.LBB0_150:
	s_and_b32 s27, s37, 0x10000
	s_xor_b32 s38, s27, 0x10000
	s_add_i32 s27, s27, 0
	s_add_i32 s101, s100, s38
	s_cmpk_eq_i32 s4, 0
	s_cbranch_scc1 .Lg1n_150
	s_waitcnt lgkmcnt(3)
	v_mfma_f32_16x16x32_bf16 v[124:127], v[160:163], v[180:183], v[124:127]
	v_mfma_f32_16x16x32_bf16 v[108:111], v[168:171], v[180:183], v[108:111]
	v_mfma_f32_16x16x32_bf16 v[92:95], v[172:175], v[180:183], v[92:95]
	v_mfma_f32_16x16x32_bf16 v[76:79], v[176:179], v[180:183], v[76:79]
	s_add_i32 m0, s101, 0x4000
	ds_read_b128 v[240:243], v200
	ds_read_b128 v[244:247], v201
	global_load_lds_dwordx4 v142, s[98:99]
	s_waitcnt lgkmcnt(4)
	v_mfma_f32_16x16x32_bf16 v[120:123], v[160:163], v[184:187], v[120:123]
	v_mfma_f32_16x16x32_bf16 v[104:107], v[168:171], v[184:187], v[104:107]
	v_mfma_f32_16x16x32_bf16 v[88:91], v[172:175], v[184:187], v[88:91]
	v_mfma_f32_16x16x32_bf16 v[72:75], v[176:179], v[184:187], v[72:75]
	s_add_i32 m0, s101, 0xc000
	ds_read_b128 v[248:251], v202
	ds_read_b128 v[252:255], v203
	global_load_lds_dwordx4 v130, vcc
	s_waitcnt lgkmcnt(5)
	v_mfma_f32_16x16x32_bf16 v[116:119], v[160:163], v[188:191], v[116:119]
	v_mfma_f32_16x16x32_bf16 v[100:103], v[168:171], v[188:191], v[100:103]
	v_mfma_f32_16x16x32_bf16 v[84:87], v[172:175], v[188:191], v[84:87]
	s_add_i32 m0, s101, 0x6000
	v_mfma_f32_16x16x32_bf16 v[68:71], v[176:179], v[188:191], v[68:71]
	global_load_lds_dwordx4 v140, s[98:99]
	s_waitcnt lgkmcnt(4)
	v_mfma_f32_16x16x32_bf16 v[112:115], v[160:163], v[192:195], v[112:115]
	v_mfma_f32_16x16x32_bf16 v[96:99], v[168:171], v[192:195], v[96:99]
	v_mfma_f32_16x16x32_bf16 v[80:83], v[172:175], v[192:195], v[80:83]
	s_add_i32 m0, s101, 0xe000
	v_mfma_f32_16x16x32_bf16 v[64:67], v[176:179], v[192:195], v[64:67]
	global_load_lds_dwordx4 v128, vcc

.Lg2b_150:
	s_waitcnt lgkmcnt(3)
	v_mfma_f32_16x16x32_bf16 v[124:127], v[160:163], v[180:183], v[124:127]
	v_mfma_f32_16x16x32_bf16 v[108:111], v[168:171], v[180:183], v[108:111]
	v_mfma_f32_16x16x32_bf16 v[92:95], v[172:175], v[180:183], v[92:95]
	v_mfma_f32_16x16x32_bf16 v[76:79], v[176:179], v[180:183], v[76:79]
	ds_read_b128 v[240:243], v200 offset:1024
	ds_read_b128 v[244:247], v201 offset:1024
	s_waitcnt lgkmcnt(4)
	v_mfma_f32_16x16x32_bf16 v[120:123], v[160:163], v[184:187], v[120:123]
	v_mfma_f32_16x16x32_bf16 v[104:107], v[168:171], v[184:187], v[104:107]
	v_mfma_f32_16x16x32_bf16 v[88:91], v[172:175], v[184:187], v[88:91]
	v_mfma_f32_16x16x32_bf16 v[72:75], v[176:179], v[184:187], v[72:75]
	ds_read_b128 v[248:251], v202 offset:1024
	ds_read_b128 v[252:255], v203 offset:1024
	s_waitcnt lgkmcnt(5)
	v_mfma_f32_16x16x32_bf16 v[116:119], v[160:163], v[188:191], v[116:119]
	v_mfma_f32_16x16x32_bf16 v[100:103], v[168:171], v[188:191], v[100:103]
	v_mfma_f32_16x16x32_bf16 v[84:87], v[172:175], v[188:191], v[84:87]
	v_mfma_f32_16x16x32_bf16 v[68:71], v[176:179], v[188:191], v[68:71]
	s_waitcnt lgkmcnt(4)
	v_mfma_f32_16x16x32_bf16 v[112:115], v[160:163], v[192:195], v[112:115]
	v_mfma_f32_16x16x32_bf16 v[96:99], v[168:171], v[192:195], v[96:99]
	v_mfma_f32_16x16x32_bf16 v[80:83], v[172:175], v[192:195], v[80:83]
	v_mfma_f32_16x16x32_bf16 v[64:67], v[176:179], v[192:195], v[64:67]
	s_add_i32 s101, s100, s27
	s_cmpk_eq_i32 s4, 0x700
	s_cbranch_scc1 .Lg4n_150
	s_waitcnt vmcnt(0) lgkmcnt(0)
	s_barrier
	s_add_u32 s98, s98, 0x80
	s_addc_u32 s99, s99, 0
	s_add_u32 vcc_lo, vcc_lo, 0x80
	s_addc_u32 vcc_hi, vcc_hi, 0
	v_mfma_f32_16x16x32_bf16 v[60:63], v[240:243], v[180:183], v[60:63]
	v_mfma_f32_16x16x32_bf16 v[44:47], v[244:247], v[180:183], v[44:47]
	v_mfma_f32_16x16x32_bf16 v[16:19], v[248:251], v[180:183], v[16:19]
	v_mfma_f32_16x16x32_bf16 v[36:39], v[252:255], v[180:183], v[36:39]
	s_mov_b32 m0, s101
	v_add3_u32 v134, s38, v149, v150
	ds_read_b128 v[180:183], v134 offset:32768
	v_add3_u32 v196, s38, v149, v151
	v_add3_u32 v197, s38, v153, v152
	v_add3_u32 v198, s38, v153, v154
	v_add3_u32 v199, s38, v153, v155
	ds_read_b128 v[160:163], v196
	ds_read_b128 v[168:171], v197
	ds_read_b128 v[172:175], v198
	ds_read_b128 v[176:179], v199
	global_load_lds_dwordx4 v146, s[98:99]
	v_mfma_f32_16x16x32_bf16 v[56:59], v[240:243], v[184:187], v[56:59]
	v_mfma_f32_16x16x32_bf16 v[40:43], v[244:247], v[184:187], v[40:43]
	v_mfma_f32_16x16x32_bf16 v[12:15], v[248:251], v[184:187], v[12:15]
	v_mfma_f32_16x16x32_bf16 v[28:31], v[252:255], v[184:187], v[28:31]
	s_add_i32 m0, s101, 0x8000
	ds_read_b128 v[184:187], v134 offset:34816
	v_add3_u32 v200, s38, v153, v156
	v_add3_u32 v201, s38, v153, v157
	v_add3_u32 v202, s38, v153, v158
	v_add3_u32 v203, s38, v153, v159
	global_load_lds_dwordx4 v138, vcc
	v_mfma_f32_16x16x32_bf16 v[52:55], v[240:243], v[188:191], v[52:55]
	v_mfma_f32_16x16x32_bf16 v[32:35], v[244:247], v[188:191], v[32:35]
	v_mfma_f32_16x16x32_bf16 v[4:7], v[248:251], v[188:191], v[4:7]
	v_mfma_f32_16x16x32_bf16 v[20:23], v[252:255], v[188:191], v[20:23]
	s_add_i32 m0, s101, 0x2000
	ds_read_b128 v[188:191], v134 offset:36864
	global_load_lds_dwordx4 v144, s[98:99]
	v_mfma_f32_16x16x32_bf16 v[48:51], v[240:243], v[192:195], v[48:51]
	v_mfma_f32_16x16x32_bf16 v[24:27], v[244:247], v[192:195], v[24:27]
	v_mfma_f32_16x16x32_bf16 v[0:3], v[248:251], v[192:195], v[0:3]
	v_mfma_f32_16x16x32_bf16 v[8:11], v[252:255], v[192:195], v[8:11]
	s_add_i32 m0, s101, 0xa000
	ds_read_b128 v[192:195], v134 offset:38912
	global_load_lds_dwordx4 v136, vcc

.LBB0_165:
	s_and_b32 s27, s6, 0x10000
	s_xor_b32 s34, s27, 0x10000
	s_add_i32 s27, s27, 0
	s_add_i32 s101, s100, s34
	s_cmpk_eq_i32 s30, 0
	s_cbranch_scc1 .Lg1n_165
	s_waitcnt lgkmcnt(3)
	v_mfma_f32_16x16x32_bf16 v[108:111], v[184:187], v[168:171], v[108:111]
	v_mfma_f32_16x16x32_bf16 v[92:95], v[184:187], v[172:175], v[92:95]
	v_mfma_f32_16x16x32_bf16 v[76:79], v[184:187], v[176:179], v[76:79]
	v_mfma_f32_16x16x32_bf16 v[60:63], v[184:187], v[180:183], v[60:63]
	s_add_i32 m0, s101, 0x4000
	ds_read_b128 v[240:243], v202
	ds_read_b128 v[244:247], v203
	global_load_lds_dwordx4 v144, s[98:99]
	s_waitcnt lgkmcnt(4)
	v_mfma_f32_16x16x32_bf16 v[104:107], v[188:191], v[168:171], v[104:107]
	v_mfma_f32_16x16x32_bf16 v[88:91], v[188:191], v[172:175], v[88:91]
	v_mfma_f32_16x16x32_bf16 v[72:75], v[188:191], v[176:179], v[72:75]
	v_mfma_f32_16x16x32_bf16 v[56:59], v[188:191], v[180:183], v[56:59]
	s_add_i32 m0, s101, 0xc000
	ds_read_b128 v[248:251], v204
	ds_read_b128 v[252:255], v205
	global_load_lds_dwordx4 v136, vcc
	s_waitcnt lgkmcnt(5)
	v_mfma_f32_16x16x32_bf16 v[100:103], v[192:195], v[168:171], v[100:103]
	v_mfma_f32_16x16x32_bf16 v[84:87], v[192:195], v[172:175], v[84:87]
	v_mfma_f32_16x16x32_bf16 v[68:71], v[192:195], v[176:179], v[68:71]
	s_add_i32 m0, s101, 0x6000
	v_mfma_f32_16x16x32_bf16 v[52:55], v[192:195], v[180:183], v[52:55]
	global_load_lds_dwordx4 v142, s[98:99]
	s_waitcnt lgkmcnt(4)
	v_mfma_f32_16x16x32_bf16 v[96:99], v[196:199], v[168:171], v[96:99]
	v_mfma_f32_16x16x32_bf16 v[80:83], v[196:199], v[172:175], v[80:83]
	v_mfma_f32_16x16x32_bf16 v[64:67], v[196:199], v[176:179], v[64:67]
	s_add_i32 m0, s101, 0xe000
	v_mfma_f32_16x16x32_bf16 v[48:51], v[196:199], v[180:183], v[48:51]
	global_load_lds_dwordx4 v130, vcc

.Lg2b_165:
	s_waitcnt lgkmcnt(3)
	v_mfma_f32_16x16x32_bf16 v[108:111], v[184:187], v[168:171], v[108:111]
	v_mfma_f32_16x16x32_bf16 v[92:95], v[184:187], v[172:175], v[92:95]
	v_mfma_f32_16x16x32_bf16 v[76:79], v[184:187], v[176:179], v[76:79]
	v_mfma_f32_16x16x32_bf16 v[60:63], v[184:187], v[180:183], v[60:63]
	ds_read_b128 v[240:243], v202 offset:1024
	ds_read_b128 v[244:247], v203 offset:1024
	s_waitcnt lgkmcnt(4)
	v_mfma_f32_16x16x32_bf16 v[104:107], v[188:191], v[168:171], v[104:107]
	v_mfma_f32_16x16x32_bf16 v[88:91], v[188:191], v[172:175], v[88:91]
	v_mfma_f32_16x16x32_bf16 v[72:75], v[188:191], v[176:179], v[72:75]
	v_mfma_f32_16x16x32_bf16 v[56:59], v[188:191], v[180:183], v[56:59]
	ds_read_b128 v[248:251], v204 offset:1024
	ds_read_b128 v[252:255], v205 offset:1024
	s_waitcnt lgkmcnt(5)
	v_mfma_f32_16x16x32_bf16 v[100:103], v[192:195], v[168:171], v[100:103]
	v_mfma_f32_16x16x32_bf16 v[84:87], v[192:195], v[172:175], v[84:87]
	v_mfma_f32_16x16x32_bf16 v[68:71], v[192:195], v[176:179], v[68:71]
	v_mfma_f32_16x16x32_bf16 v[52:55], v[192:195], v[180:183], v[52:55]
	s_waitcnt lgkmcnt(4)
	v_mfma_f32_16x16x32_bf16 v[96:99], v[196:199], v[168:171], v[96:99]
	v_mfma_f32_16x16x32_bf16 v[80:83], v[196:199], v[172:175], v[80:83]
	v_mfma_f32_16x16x32_bf16 v[64:67], v[196:199], v[176:179], v[64:67]
	v_mfma_f32_16x16x32_bf16 v[48:51], v[196:199], v[180:183], v[48:51]
	s_add_i32 s101, s100, s27
	s_cmpk_eq_i32 s30, 0x700
	s_cbranch_scc1 .Lg4n_165
	s_waitcnt vmcnt(0) lgkmcnt(0)
	s_barrier
	s_add_u32 s98, s98, 0x80
	s_addc_u32 s99, s99, 0
	s_add_u32 vcc_lo, vcc_lo, 0x80
	s_addc_u32 vcc_hi, vcc_hi, 0
	v_mfma_f32_16x16x32_bf16 v[44:47], v[184:187], v[240:243], v[44:47]
	v_mfma_f32_16x16x32_bf16 v[28:31], v[184:187], v[244:247], v[28:31]
	v_mfma_f32_16x16x32_bf16 v[12:15], v[184:187], v[248:251], v[12:15]
	v_mfma_f32_16x16x32_bf16 v[112:115], v[184:187], v[252:255], v[112:115]
	s_mov_b32 m0, s101
	v_add3_u32 v134, s34, v151, v152
	ds_read_b128 v[184:187], v134 offset:32768
	v_add3_u32 v162, s34, v151, v153
	v_add3_u32 v163, s34, v155, v154
	v_add3_u32 v200, s34, v155, v156
	v_add3_u32 v201, s34, v155, v157
	ds_read_b128 v[168:171], v162
	ds_read_b128 v[172:175], v163
	ds_read_b128 v[176:179], v200
	ds_read_b128 v[180:183], v201
	global_load_lds_dwordx4 v148, s[98:99]
	v_mfma_f32_16x16x32_bf16 v[40:43], v[188:191], v[240:243], v[40:43]
	v_mfma_f32_16x16x32_bf16 v[24:27], v[188:191], v[244:247], v[24:27]
	v_mfma_f32_16x16x32_bf16 v[8:11], v[188:191], v[248:251], v[8:11]
	v_mfma_f32_16x16x32_bf16 v[116:119], v[188:191], v[252:255], v[116:119]
	s_add_i32 m0, s101, 0x8000
	ds_read_b128 v[188:191], v134 offset:34816
	v_add3_u32 v202, s34, v155, v158
	v_add3_u32 v203, s34, v155, v159
	v_add3_u32 v204, s34, v155, v160
	v_add3_u32 v205, s34, v155, v161
	global_load_lds_dwordx4 v140, vcc
	v_mfma_f32_16x16x32_bf16 v[36:39], v[192:195], v[240:243], v[36:39]
	v_mfma_f32_16x16x32_bf16 v[20:23], v[192:195], v[244:247], v[20:23]
	v_mfma_f32_16x16x32_bf16 v[4:7], v[192:195], v[248:251], v[4:7]
	v_mfma_f32_16x16x32_bf16 v[120:123], v[192:195], v[252:255], v[120:123]
	s_add_i32 m0, s101, 0x2000
	ds_read_b128 v[192:195], v134 offset:36864
	global_load_lds_dwordx4 v146, s[98:99]
	v_mfma_f32_16x16x32_bf16 v[32:35], v[196:199], v[240:243], v[32:35]
	v_mfma_f32_16x16x32_bf16 v[16:19], v[196:199], v[244:247], v[16:19]
	v_mfma_f32_16x16x32_bf16 v[0:3], v[196:199], v[248:251], v[0:3]
	v_mfma_f32_16x16x32_bf16 v[124:127], v[196:199], v[252:255], v[124:127]
	s_add_i32 m0, s101, 0xa000
	ds_read_b128 v[196:199], v134 offset:38912
	global_load_lds_dwordx4 v138, vcc

.LBB0_177:
	s_and_b32 s27, s6, 0x10000
	s_xor_b32 s30, s27, 0x10000
	s_add_i32 s27, s27, 0
	s_add_i32 s101, s100, s30
	s_cmpk_eq_i32 s4, 0
	s_cbranch_scc1 .Lg1n_177
	s_waitcnt lgkmcnt(3)
	v_mfma_f32_16x16x32_bf16 v[108:111], v[160:163], v[180:183], v[108:111]
	v_mfma_f32_16x16x32_bf16 v[92:95], v[168:171], v[180:183], v[92:95]
	v_mfma_f32_16x16x32_bf16 v[76:79], v[172:175], v[180:183], v[76:79]
	v_mfma_f32_16x16x32_bf16 v[60:63], v[176:179], v[180:183], v[60:63]
	s_add_i32 m0, s101, 0x4000
	ds_read_b128 v[240:243], v200
	ds_read_b128 v[244:247], v201
	global_load_lds_dwordx4 v142, s[98:99]
	s_waitcnt lgkmcnt(4)
	v_mfma_f32_16x16x32_bf16 v[104:107], v[160:163], v[184:187], v[104:107]
	v_mfma_f32_16x16x32_bf16 v[88:91], v[168:171], v[184:187], v[88:91]
	v_mfma_f32_16x16x32_bf16 v[72:75], v[172:175], v[184:187], v[72:75]
	v_mfma_f32_16x16x32_bf16 v[56:59], v[176:179], v[184:187], v[56:59]
	s_add_i32 m0, s101, 0xc000
	ds_read_b128 v[248:251], v202
	ds_read_b128 v[252:255], v203
	global_load_lds_dwordx4 v130, vcc
	s_waitcnt lgkmcnt(5)
	v_mfma_f32_16x16x32_bf16 v[100:103], v[160:163], v[188:191], v[100:103]
	v_mfma_f32_16x16x32_bf16 v[84:87], v[168:171], v[188:191], v[84:87]
	v_mfma_f32_16x16x32_bf16 v[68:71], v[172:175], v[188:191], v[68:71]
	s_add_i32 m0, s101, 0x6000
	v_mfma_f32_16x16x32_bf16 v[52:55], v[176:179], v[188:191], v[52:55]
	global_load_lds_dwordx4 v140, s[98:99]
	s_waitcnt lgkmcnt(4)
	v_mfma_f32_16x16x32_bf16 v[96:99], v[160:163], v[192:195], v[96:99]
	v_mfma_f32_16x16x32_bf16 v[80:83], v[168:171], v[192:195], v[80:83]
	v_mfma_f32_16x16x32_bf16 v[64:67], v[172:175], v[192:195], v[64:67]
	s_add_i32 m0, s101, 0xe000
	v_mfma_f32_16x16x32_bf16 v[48:51], v[176:179], v[192:195], v[48:51]
	global_load_lds_dwordx4 v128, vcc

.Lg2b_177:
	s_waitcnt lgkmcnt(3)
	v_mfma_f32_16x16x32_bf16 v[108:111], v[160:163], v[180:183], v[108:111]
	v_mfma_f32_16x16x32_bf16 v[92:95], v[168:171], v[180:183], v[92:95]
	v_mfma_f32_16x16x32_bf16 v[76:79], v[172:175], v[180:183], v[76:79]
	v_mfma_f32_16x16x32_bf16 v[60:63], v[176:179], v[180:183], v[60:63]
	ds_read_b128 v[240:243], v200 offset:1024
	ds_read_b128 v[244:247], v201 offset:1024
	s_waitcnt lgkmcnt(4)
	v_mfma_f32_16x16x32_bf16 v[104:107], v[160:163], v[184:187], v[104:107]
	v_mfma_f32_16x16x32_bf16 v[88:91], v[168:171], v[184:187], v[88:91]
	v_mfma_f32_16x16x32_bf16 v[72:75], v[172:175], v[184:187], v[72:75]
	v_mfma_f32_16x16x32_bf16 v[56:59], v[176:179], v[184:187], v[56:59]
	ds_read_b128 v[248:251], v202 offset:1024
	ds_read_b128 v[252:255], v203 offset:1024
	s_waitcnt lgkmcnt(5)
	v_mfma_f32_16x16x32_bf16 v[100:103], v[160:163], v[188:191], v[100:103]
	v_mfma_f32_16x16x32_bf16 v[84:87], v[168:171], v[188:191], v[84:87]
	v_mfma_f32_16x16x32_bf16 v[68:71], v[172:175], v[188:191], v[68:71]
	v_mfma_f32_16x16x32_bf16 v[52:55], v[176:179], v[188:191], v[52:55]
	s_waitcnt lgkmcnt(4)
	v_mfma_f32_16x16x32_bf16 v[96:99], v[160:163], v[192:195], v[96:99]
	v_mfma_f32_16x16x32_bf16 v[80:83], v[168:171], v[192:195], v[80:83]
	v_mfma_f32_16x16x32_bf16 v[64:67], v[172:175], v[192:195], v[64:67]
	v_mfma_f32_16x16x32_bf16 v[48:51], v[176:179], v[192:195], v[48:51]
	s_add_i32 s101, s100, s27
	s_cmpk_eq_i32 s4, 0x700
	s_cbranch_scc1 .Lg4n_177
	s_waitcnt vmcnt(0) lgkmcnt(0)
	s_barrier
	s_add_u32 s98, s98, 0x80
	s_addc_u32 s99, s99, 0
	s_add_u32 vcc_lo, vcc_lo, 0x80
	s_addc_u32 vcc_hi, vcc_hi, 0
	v_mfma_f32_16x16x32_bf16 v[44:47], v[240:243], v[180:183], v[44:47]
	v_mfma_f32_16x16x32_bf16 v[28:31], v[244:247], v[180:183], v[28:31]
	v_mfma_f32_16x16x32_bf16 v[12:15], v[248:251], v[180:183], v[12:15]
	v_mfma_f32_16x16x32_bf16 v[112:115], v[252:255], v[180:183], v[112:115]
	s_mov_b32 m0, s101
	v_add3_u32 v134, s30, v149, v150
	ds_read_b128 v[180:183], v134 offset:32768
	v_add3_u32 v196, s30, v149, v151
	v_add3_u32 v197, s30, v153, v152
	v_add3_u32 v198, s30, v153, v154
	v_add3_u32 v199, s30, v153, v155
	ds_read_b128 v[160:163], v196
	ds_read_b128 v[168:171], v197
	ds_read_b128 v[172:175], v198
	ds_read_b128 v[176:179], v199
	global_load_lds_dwordx4 v146, s[98:99]
	v_mfma_f32_16x16x32_bf16 v[40:43], v[240:243], v[184:187], v[40:43]
	v_mfma_f32_16x16x32_bf16 v[24:27], v[244:247], v[184:187], v[24:27]
	v_mfma_f32_16x16x32_bf16 v[8:11], v[248:251], v[184:187], v[8:11]
	v_mfma_f32_16x16x32_bf16 v[116:119], v[252:255], v[184:187], v[116:119]
	s_add_i32 m0, s101, 0x8000
	ds_read_b128 v[184:187], v134 offset:34816
	v_add3_u32 v200, s30, v153, v156
	v_add3_u32 v201, s30, v153, v157
	v_add3_u32 v202, s30, v153, v158
	v_add3_u32 v203, s30, v153, v159
	global_load_lds_dwordx4 v138, vcc
	v_mfma_f32_16x16x32_bf16 v[36:39], v[240:243], v[188:191], v[36:39]
	v_mfma_f32_16x16x32_bf16 v[20:23], v[244:247], v[188:191], v[20:23]
	v_mfma_f32_16x16x32_bf16 v[4:7], v[248:251], v[188:191], v[4:7]
	v_mfma_f32_16x16x32_bf16 v[120:123], v[252:255], v[188:191], v[120:123]
	s_add_i32 m0, s101, 0x2000
	ds_read_b128 v[188:191], v134 offset:36864
	global_load_lds_dwordx4 v144, s[98:99]
	v_mfma_f32_16x16x32_bf16 v[32:35], v[240:243], v[192:195], v[32:35]
	v_mfma_f32_16x16x32_bf16 v[16:19], v[244:247], v[192:195], v[16:19]
	v_mfma_f32_16x16x32_bf16 v[0:3], v[248:251], v[192:195], v[0:3]
	v_mfma_f32_16x16x32_bf16 v[124:127], v[252:255], v[192:195], v[124:127]
	s_add_i32 m0, s101, 0xa000
	ds_read_b128 v[192:195], v134 offset:38912
	global_load_lds_dwordx4 v136, vcc

.LBB0_181:
	s_and_b32 s27, s6, 0x10000
	s_xor_b32 s28, s27, 0x10000
	s_add_i32 s27, s27, 0
	s_add_i32 s101, s100, s28
	s_cmpk_eq_i32 s4, 0
	s_cbranch_scc1 .Lg1n_181
	s_waitcnt lgkmcnt(3)
	v_mfma_f32_16x16x32_bf16 v[124:127], v[184:187], v[168:171], v[124:127]
	v_mfma_f32_16x16x32_bf16 v[108:111], v[184:187], v[172:175], v[108:111]
	v_mfma_f32_16x16x32_bf16 v[92:95], v[184:187], v[176:179], v[92:95]
	v_mfma_f32_16x16x32_bf16 v[76:79], v[184:187], v[180:183], v[76:79]
	s_add_i32 m0, s101, 0x4000
	ds_read_b128 v[240:243], v202
	ds_read_b128 v[244:247], v203
	global_load_lds_dwordx4 v144, s[98:99]
	s_waitcnt lgkmcnt(4)
	v_mfma_f32_16x16x32_bf16 v[120:123], v[188:191], v[168:171], v[120:123]
	v_mfma_f32_16x16x32_bf16 v[104:107], v[188:191], v[172:175], v[104:107]
	v_mfma_f32_16x16x32_bf16 v[88:91], v[188:191], v[176:179], v[88:91]
	v_mfma_f32_16x16x32_bf16 v[72:75], v[188:191], v[180:183], v[72:75]
	s_add_i32 m0, s101, 0xc000
	ds_read_b128 v[248:251], v204
	ds_read_b128 v[252:255], v205
	global_load_lds_dwordx4 v136, vcc
	s_waitcnt lgkmcnt(5)
	v_mfma_f32_16x16x32_bf16 v[116:119], v[192:195], v[168:171], v[116:119]
	v_mfma_f32_16x16x32_bf16 v[100:103], v[192:195], v[172:175], v[100:103]
	v_mfma_f32_16x16x32_bf16 v[84:87], v[192:195], v[176:179], v[84:87]
	s_add_i32 m0, s101, 0x6000
	v_mfma_f32_16x16x32_bf16 v[68:71], v[192:195], v[180:183], v[68:71]
	global_load_lds_dwordx4 v142, s[98:99]
	s_waitcnt lgkmcnt(4)
	v_mfma_f32_16x16x32_bf16 v[112:115], v[196:199], v[168:171], v[112:115]
	v_mfma_f32_16x16x32_bf16 v[96:99], v[196:199], v[172:175], v[96:99]
	v_mfma_f32_16x16x32_bf16 v[80:83], v[196:199], v[176:179], v[80:83]
	s_add_i32 m0, s101, 0xe000
	v_mfma_f32_16x16x32_bf16 v[64:67], v[196:199], v[180:183], v[64:67]
	global_load_lds_dwordx4 v130, vcc

.Lg2b_181:
	s_waitcnt lgkmcnt(3)
	v_mfma_f32_16x16x32_bf16 v[124:127], v[184:187], v[168:171], v[124:127]
	v_mfma_f32_16x16x32_bf16 v[108:111], v[184:187], v[172:175], v[108:111]
	v_mfma_f32_16x16x32_bf16 v[92:95], v[184:187], v[176:179], v[92:95]
	v_mfma_f32_16x16x32_bf16 v[76:79], v[184:187], v[180:183], v[76:79]
	ds_read_b128 v[240:243], v202 offset:1024
	ds_read_b128 v[244:247], v203 offset:1024
	s_waitcnt lgkmcnt(4)
	v_mfma_f32_16x16x32_bf16 v[120:123], v[188:191], v[168:171], v[120:123]
	v_mfma_f32_16x16x32_bf16 v[104:107], v[188:191], v[172:175], v[104:107]
	v_mfma_f32_16x16x32_bf16 v[88:91], v[188:191], v[176:179], v[88:91]
	v_mfma_f32_16x16x32_bf16 v[72:75], v[188:191], v[180:183], v[72:75]
	ds_read_b128 v[248:251], v204 offset:1024
	ds_read_b128 v[252:255], v205 offset:1024
	s_waitcnt lgkmcnt(5)
	v_mfma_f32_16x16x32_bf16 v[116:119], v[192:195], v[168:171], v[116:119]
	v_mfma_f32_16x16x32_bf16 v[100:103], v[192:195], v[172:175], v[100:103]
	v_mfma_f32_16x16x32_bf16 v[84:87], v[192:195], v[176:179], v[84:87]
	v_mfma_f32_16x16x32_bf16 v[68:71], v[192:195], v[180:183], v[68:71]
	s_waitcnt lgkmcnt(4)
	v_mfma_f32_16x16x32_bf16 v[112:115], v[196:199], v[168:171], v[112:115]
	v_mfma_f32_16x16x32_bf16 v[96:99], v[196:199], v[172:175], v[96:99]
	v_mfma_f32_16x16x32_bf16 v[80:83], v[196:199], v[176:179], v[80:83]
	v_mfma_f32_16x16x32_bf16 v[64:67], v[196:199], v[180:183], v[64:67]
	s_add_i32 s101, s100, s27
	s_cmpk_eq_i32 s4, 0x700
	s_cbranch_scc1 .Lg4n_181
	s_waitcnt vmcnt(0) lgkmcnt(0)
	s_barrier
	s_add_u32 s98, s98, 0x80
	s_addc_u32 s99, s99, 0
	s_add_u32 vcc_lo, vcc_lo, 0x80
	s_addc_u32 vcc_hi, vcc_hi, 0
	v_mfma_f32_16x16x32_bf16 v[60:63], v[184:187], v[240:243], v[60:63]
	v_mfma_f32_16x16x32_bf16 v[44:47], v[184:187], v[244:247], v[44:47]
	v_mfma_f32_16x16x32_bf16 v[16:19], v[184:187], v[248:251], v[16:19]
	v_mfma_f32_16x16x32_bf16 v[36:39], v[184:187], v[252:255], v[36:39]
	s_mov_b32 m0, s101
	v_add3_u32 v161, s28, v151, v152
	ds_read_b128 v[184:187], v161 offset:32768
	v_add3_u32 v162, s28, v151, v153
	v_add3_u32 v163, s28, v154, v134
	v_add3_u32 v200, s28, v154, v155
	v_add3_u32 v201, s28, v154, v156
	ds_read_b128 v[168:171], v162
	ds_read_b128 v[172:175], v163
	ds_read_b128 v[176:179], v200
	ds_read_b128 v[180:183], v201
	global_load_lds_dwordx4 v148, s[98:99]
	v_mfma_f32_16x16x32_bf16 v[56:59], v[188:191], v[240:243], v[56:59]
	v_mfma_f32_16x16x32_bf16 v[40:43], v[188:191], v[244:247], v[40:43]
	v_mfma_f32_16x16x32_bf16 v[12:15], v[188:191], v[248:251], v[12:15]
	v_mfma_f32_16x16x32_bf16 v[28:31], v[188:191], v[252:255], v[28:31]
	s_add_i32 m0, s101, 0x8000
	ds_read_b128 v[188:191], v161 offset:34816
	v_add3_u32 v202, s28, v154, v157
	v_add3_u32 v203, s28, v154, v158
	v_add3_u32 v204, s28, v154, v159
	v_add3_u32 v205, s28, v154, v160
	global_load_lds_dwordx4 v140, vcc
	v_mfma_f32_16x16x32_bf16 v[52:55], v[192:195], v[240:243], v[52:55]
	v_mfma_f32_16x16x32_bf16 v[32:35], v[192:195], v[244:247], v[32:35]
	v_mfma_f32_16x16x32_bf16 v[4:7], v[192:195], v[248:251], v[4:7]
	v_mfma_f32_16x16x32_bf16 v[20:23], v[192:195], v[252:255], v[20:23]
	s_add_i32 m0, s101, 0x2000
	ds_read_b128 v[192:195], v161 offset:36864
	global_load_lds_dwordx4 v146, s[98:99]
	v_mfma_f32_16x16x32_bf16 v[48:51], v[196:199], v[240:243], v[48:51]
	v_mfma_f32_16x16x32_bf16 v[24:27], v[196:199], v[244:247], v[24:27]
	v_mfma_f32_16x16x32_bf16 v[0:3], v[196:199], v[248:251], v[0:3]
	v_mfma_f32_16x16x32_bf16 v[8:11], v[196:199], v[252:255], v[8:11]
	s_add_i32 m0, s101, 0xa000
	ds_read_b128 v[196:199], v161 offset:38912
	global_load_lds_dwordx4 v138, vcc

.LBB0_793:
	s_and_b32 s31, s0, 0x10000
	s_xor_b32 s42, s31, 0x10000
	s_add_i32 s31, s31, 0
	s_add_i32 s101, s100, s42
	s_cmpk_eq_i32 s38, 0
	s_cbranch_scc1 .Lg1n_793
	s_waitcnt lgkmcnt(3)
	v_mfma_f32_16x16x32_bf16 v[126:129], v[180:183], v[164:167], v[126:129]
	v_mfma_f32_16x16x32_bf16 v[110:113], v[180:183], v[168:171], v[110:113]
	v_mfma_f32_16x16x32_bf16 v[94:97], v[180:183], v[172:175], v[94:97]
	v_mfma_f32_16x16x32_bf16 v[78:81], v[180:183], v[176:179], v[78:81]
	s_add_i32 m0, s101, 0x4000
	ds_read_b128 v[240:243], v199
	ds_read_b128 v[244:247], v200
	global_load_lds_dwordx4 v144, s[98:99]
	s_waitcnt lgkmcnt(4)
	v_mfma_f32_16x16x32_bf16 v[122:125], v[184:187], v[164:167], v[122:125]
	v_mfma_f32_16x16x32_bf16 v[106:109], v[184:187], v[168:171], v[106:109]
	v_mfma_f32_16x16x32_bf16 v[90:93], v[184:187], v[172:175], v[90:93]
	v_mfma_f32_16x16x32_bf16 v[74:77], v[184:187], v[176:179], v[74:77]
	s_add_i32 m0, s101, 0xc000
	ds_read_b128 v[248:251], v201
	ds_read_b128 v[252:255], v202
	global_load_lds_dwordx4 v136, vcc
	s_waitcnt lgkmcnt(5)
	v_mfma_f32_16x16x32_bf16 v[118:121], v[188:191], v[164:167], v[118:121]
	v_mfma_f32_16x16x32_bf16 v[102:105], v[188:191], v[168:171], v[102:105]
	v_mfma_f32_16x16x32_bf16 v[86:89], v[188:191], v[172:175], v[86:89]
	s_add_i32 m0, s101, 0x6000
	v_mfma_f32_16x16x32_bf16 v[70:73], v[188:191], v[176:179], v[70:73]
	global_load_lds_dwordx4 v142, s[98:99]
	s_waitcnt lgkmcnt(4)
	v_mfma_f32_16x16x32_bf16 v[114:117], v[192:195], v[164:167], v[114:117]
	v_mfma_f32_16x16x32_bf16 v[98:101], v[192:195], v[168:171], v[98:101]
	v_mfma_f32_16x16x32_bf16 v[82:85], v[192:195], v[172:175], v[82:85]
	s_add_i32 m0, s101, 0xe000
	v_mfma_f32_16x16x32_bf16 v[66:69], v[192:195], v[176:179], v[66:69]
	global_load_lds_dwordx4 v134, vcc

.Lg2b_793:
	s_waitcnt lgkmcnt(3)
	v_mfma_f32_16x16x32_bf16 v[126:129], v[180:183], v[164:167], v[126:129]
	v_mfma_f32_16x16x32_bf16 v[110:113], v[180:183], v[168:171], v[110:113]
	v_mfma_f32_16x16x32_bf16 v[94:97], v[180:183], v[172:175], v[94:97]
	v_mfma_f32_16x16x32_bf16 v[78:81], v[180:183], v[176:179], v[78:81]
	ds_read_b128 v[240:243], v199 offset:1024
	ds_read_b128 v[244:247], v200 offset:1024
	s_waitcnt lgkmcnt(4)
	v_mfma_f32_16x16x32_bf16 v[122:125], v[184:187], v[164:167], v[122:125]
	v_mfma_f32_16x16x32_bf16 v[106:109], v[184:187], v[168:171], v[106:109]
	v_mfma_f32_16x16x32_bf16 v[90:93], v[184:187], v[172:175], v[90:93]
	v_mfma_f32_16x16x32_bf16 v[74:77], v[184:187], v[176:179], v[74:77]
	ds_read_b128 v[248:251], v201 offset:1024
	ds_read_b128 v[252:255], v202 offset:1024
	s_waitcnt lgkmcnt(5)
	v_mfma_f32_16x16x32_bf16 v[118:121], v[188:191], v[164:167], v[118:121]
	v_mfma_f32_16x16x32_bf16 v[102:105], v[188:191], v[168:171], v[102:105]
	v_mfma_f32_16x16x32_bf16 v[86:89], v[188:191], v[172:175], v[86:89]
	v_mfma_f32_16x16x32_bf16 v[70:73], v[188:191], v[176:179], v[70:73]
	s_waitcnt lgkmcnt(4)
	v_mfma_f32_16x16x32_bf16 v[114:117], v[192:195], v[164:167], v[114:117]
	v_mfma_f32_16x16x32_bf16 v[98:101], v[192:195], v[168:171], v[98:101]
	v_mfma_f32_16x16x32_bf16 v[82:85], v[192:195], v[172:175], v[82:85]
	v_mfma_f32_16x16x32_bf16 v[66:69], v[192:195], v[176:179], v[66:69]
	s_add_i32 s101, s100, s31
	s_cmpk_eq_i32 s38, 0x700
	s_cbranch_scc1 .Lg4n_793
	s_waitcnt vmcnt(0) lgkmcnt(0)
	s_barrier
	s_add_u32 s98, s98, 0x80
	s_addc_u32 s99, s99, 0
	s_add_u32 vcc_lo, vcc_lo, 0x80
	s_addc_u32 vcc_hi, vcc_hi, 0
	v_mfma_f32_16x16x32_bf16 v[62:65], v[180:183], v[240:243], v[62:65]
	v_mfma_f32_16x16x32_bf16 v[46:49], v[180:183], v[244:247], v[46:49]
	v_mfma_f32_16x16x32_bf16 v[18:21], v[180:183], v[248:251], v[18:21]
	v_mfma_f32_16x16x32_bf16 v[38:41], v[180:183], v[252:255], v[38:41]
	s_mov_b32 m0, s101
	v_add3_u32 v130, s42, v152, v153
	ds_read_b128 v[180:183], v130 offset:32768
	v_add3_u32 v163, s42, v152, v154
	v_add3_u32 v196, s42, v156, v155
	v_add3_u32 v197, s42, v156, v157
	v_add3_u32 v198, s42, v156, v158
	ds_read_b128 v[164:167], v163
	ds_read_b128 v[168:171], v196
	ds_read_b128 v[172:175], v197
	ds_read_b128 v[176:179], v198
	global_load_lds_dwordx4 v148, s[98:99]
	v_mfma_f32_16x16x32_bf16 v[58:61], v[184:187], v[240:243], v[58:61]
	v_mfma_f32_16x16x32_bf16 v[42:45], v[184:187], v[244:247], v[42:45]
	v_mfma_f32_16x16x32_bf16 v[10:13], v[184:187], v[248:251], v[10:13]
	v_mfma_f32_16x16x32_bf16 v[30:33], v[184:187], v[252:255], v[30:33]
	s_add_i32 m0, s101, 0x8000
	ds_read_b128 v[184:187], v130 offset:34816
	v_add3_u32 v199, s42, v156, v159
	v_add3_u32 v200, s42, v156, v160
	v_add3_u32 v201, s42, v156, v161
	v_add3_u32 v202, s42, v156, v162
	global_load_lds_dwordx4 v140, vcc
	v_mfma_f32_16x16x32_bf16 v[54:57], v[188:191], v[240:243], v[54:57]
	v_mfma_f32_16x16x32_bf16 v[34:37], v[188:191], v[244:247], v[34:37]
	v_mfma_f32_16x16x32_bf16 v[6:9], v[188:191], v[248:251], v[6:9]
	v_mfma_f32_16x16x32_bf16 v[22:25], v[188:191], v[252:255], v[22:25]
	s_add_i32 m0, s101, 0x2000
	ds_read_b128 v[188:191], v130 offset:36864
	global_load_lds_dwordx4 v146, s[98:99]
	v_mfma_f32_16x16x32_bf16 v[50:53], v[192:195], v[240:243], v[50:53]
	v_mfma_f32_16x16x32_bf16 v[26:29], v[192:195], v[244:247], v[26:29]
	v_mfma_f32_16x16x32_bf16 v[2:5], v[192:195], v[248:251], v[2:5]
	v_mfma_f32_16x16x32_bf16 v[14:17], v[192:195], v[252:255], v[14:17]
	s_add_i32 m0, s101, 0xa000
	ds_read_b128 v[192:195], v130 offset:38912
	global_load_lds_dwordx4 v138, vcc

.LBB0_795:
	s_and_b32 s0, s29, 0x10000
	s_xor_b32 s53, s0, 0x10000
	s_add_i32 s0, s0, 0
	s_add_i32 s101, s100, s53
	s_cmpk_eq_i32 s42, 0
	s_cbranch_scc1 .Lg1n_795
	s_waitcnt lgkmcnt(3)
	v_mfma_f32_16x16x32_bf16 v[124:127], v[180:183], v[164:167], v[124:127]
	v_mfma_f32_16x16x32_bf16 v[108:111], v[180:183], v[168:171], v[108:111]
	v_mfma_f32_16x16x32_bf16 v[92:95], v[180:183], v[172:175], v[92:95]
	v_mfma_f32_16x16x32_bf16 v[76:79], v[180:183], v[176:179], v[76:79]
	s_add_i32 m0, s101, 0x4000
	ds_read_b128 v[240:243], v199
	ds_read_b128 v[244:247], v200
	global_load_lds_dwordx4 v144, s[98:99]
	s_waitcnt lgkmcnt(4)
	v_mfma_f32_16x16x32_bf16 v[120:123], v[184:187], v[164:167], v[120:123]
	v_mfma_f32_16x16x32_bf16 v[104:107], v[184:187], v[168:171], v[104:107]
	v_mfma_f32_16x16x32_bf16 v[88:91], v[184:187], v[172:175], v[88:91]
	v_mfma_f32_16x16x32_bf16 v[72:75], v[184:187], v[176:179], v[72:75]
	s_add_i32 m0, s101, 0xc000
	ds_read_b128 v[248:251], v201
	ds_read_b128 v[252:255], v202
	global_load_lds_dwordx4 v136, vcc
	s_waitcnt lgkmcnt(5)
	v_mfma_f32_16x16x32_bf16 v[116:119], v[188:191], v[164:167], v[116:119]
	v_mfma_f32_16x16x32_bf16 v[100:103], v[188:191], v[168:171], v[100:103]
	v_mfma_f32_16x16x32_bf16 v[84:87], v[188:191], v[172:175], v[84:87]
	s_add_i32 m0, s101, 0x6000
	v_mfma_f32_16x16x32_bf16 v[68:71], v[188:191], v[176:179], v[68:71]
	global_load_lds_dwordx4 v142, s[98:99]
	s_waitcnt lgkmcnt(4)
	v_mfma_f32_16x16x32_bf16 v[112:115], v[192:195], v[164:167], v[112:115]
	v_mfma_f32_16x16x32_bf16 v[96:99], v[192:195], v[168:171], v[96:99]
	v_mfma_f32_16x16x32_bf16 v[80:83], v[192:195], v[172:175], v[80:83]
	s_add_i32 m0, s101, 0xe000
	v_mfma_f32_16x16x32_bf16 v[64:67], v[192:195], v[176:179], v[64:67]
	global_load_lds_dwordx4 v134, vcc

.Lg2b_795:
	s_waitcnt lgkmcnt(3)
	v_mfma_f32_16x16x32_bf16 v[124:127], v[180:183], v[164:167], v[124:127]
	v_mfma_f32_16x16x32_bf16 v[108:111], v[180:183], v[168:171], v[108:111]
	v_mfma_f32_16x16x32_bf16 v[92:95], v[180:183], v[172:175], v[92:95]
	v_mfma_f32_16x16x32_bf16 v[76:79], v[180:183], v[176:179], v[76:79]
	ds_read_b128 v[240:243], v199 offset:1024
	ds_read_b128 v[244:247], v200 offset:1024
	s_waitcnt lgkmcnt(4)
	v_mfma_f32_16x16x32_bf16 v[120:123], v[184:187], v[164:167], v[120:123]
	v_mfma_f32_16x16x32_bf16 v[104:107], v[184:187], v[168:171], v[104:107]
	v_mfma_f32_16x16x32_bf16 v[88:91], v[184:187], v[172:175], v[88:91]
	v_mfma_f32_16x16x32_bf16 v[72:75], v[184:187], v[176:179], v[72:75]
	ds_read_b128 v[248:251], v201 offset:1024
	ds_read_b128 v[252:255], v202 offset:1024
	s_waitcnt lgkmcnt(5)
	v_mfma_f32_16x16x32_bf16 v[116:119], v[188:191], v[164:167], v[116:119]
	v_mfma_f32_16x16x32_bf16 v[100:103], v[188:191], v[168:171], v[100:103]
	v_mfma_f32_16x16x32_bf16 v[84:87], v[188:191], v[172:175], v[84:87]
	v_mfma_f32_16x16x32_bf16 v[68:71], v[188:191], v[176:179], v[68:71]
	s_waitcnt lgkmcnt(4)
	v_mfma_f32_16x16x32_bf16 v[112:115], v[192:195], v[164:167], v[112:115]
	v_mfma_f32_16x16x32_bf16 v[96:99], v[192:195], v[168:171], v[96:99]
	v_mfma_f32_16x16x32_bf16 v[80:83], v[192:195], v[172:175], v[80:83]
	v_mfma_f32_16x16x32_bf16 v[64:67], v[192:195], v[176:179], v[64:67]
	s_add_i32 s101, s100, s0
	s_cmpk_eq_i32 s42, 0x700
	s_cbranch_scc1 .Lg4n_795
	s_waitcnt vmcnt(0) lgkmcnt(0)
	s_barrier
	s_add_u32 s98, s98, 0x80
	s_addc_u32 s99, s99, 0
	s_add_u32 vcc_lo, vcc_lo, 0x80
	s_addc_u32 vcc_hi, vcc_hi, 0
	v_mfma_f32_16x16x32_bf16 v[60:63], v[180:183], v[240:243], v[60:63]
	v_mfma_f32_16x16x32_bf16 v[44:47], v[180:183], v[244:247], v[44:47]
	v_mfma_f32_16x16x32_bf16 v[16:19], v[180:183], v[248:251], v[16:19]
	v_mfma_f32_16x16x32_bf16 v[36:39], v[180:183], v[252:255], v[36:39]
	s_mov_b32 m0, s101
	v_add3_u32 v130, s53, v152, v153
	ds_read_b128 v[180:183], v130 offset:32768
	v_add3_u32 v163, s53, v152, v154
	v_add3_u32 v196, s53, v156, v155
	v_add3_u32 v197, s53, v156, v157
	v_add3_u32 v198, s53, v156, v158
	ds_read_b128 v[164:167], v163
	ds_read_b128 v[168:171], v196
	ds_read_b128 v[172:175], v197
	ds_read_b128 v[176:179], v198
	global_load_lds_dwordx4 v148, s[98:99]
	v_mfma_f32_16x16x32_bf16 v[56:59], v[184:187], v[240:243], v[56:59]
	v_mfma_f32_16x16x32_bf16 v[40:43], v[184:187], v[244:247], v[40:43]
	v_mfma_f32_16x16x32_bf16 v[12:15], v[184:187], v[248:251], v[12:15]
	v_mfma_f32_16x16x32_bf16 v[28:31], v[184:187], v[252:255], v[28:31]
	s_add_i32 m0, s101, 0x8000
	ds_read_b128 v[184:187], v130 offset:34816
	v_add3_u32 v199, s53, v156, v159
	v_add3_u32 v200, s53, v156, v160
	v_add3_u32 v201, s53, v156, v161
	v_add3_u32 v202, s53, v156, v162
	global_load_lds_dwordx4 v140, vcc
	v_mfma_f32_16x16x32_bf16 v[52:55], v[188:191], v[240:243], v[52:55]
	v_mfma_f32_16x16x32_bf16 v[32:35], v[188:191], v[244:247], v[32:35]
	v_mfma_f32_16x16x32_bf16 v[4:7], v[188:191], v[248:251], v[4:7]
	v_mfma_f32_16x16x32_bf16 v[20:23], v[188:191], v[252:255], v[20:23]
	s_add_i32 m0, s101, 0x2000
	ds_read_b128 v[188:191], v130 offset:36864
	global_load_lds_dwordx4 v146, s[98:99]
	v_mfma_f32_16x16x32_bf16 v[48:51], v[192:195], v[240:243], v[48:51]
	v_mfma_f32_16x16x32_bf16 v[24:27], v[192:195], v[244:247], v[24:27]
	v_mfma_f32_16x16x32_bf16 v[0:3], v[192:195], v[248:251], v[0:3]
	v_mfma_f32_16x16x32_bf16 v[8:11], v[192:195], v[252:255], v[8:11]
	s_add_i32 m0, s101, 0xa000
	ds_read_b128 v[192:195], v130 offset:38912
	global_load_lds_dwordx4 v138, vcc

.LBB0_797:
	s_and_b32 s39, s38, 0x10000
	s_xor_b32 s42, s39, 0x10000
	s_add_i32 s39, s39, 0
	s_add_i32 s101, s100, s42
	s_cmpk_eq_i32 s36, 0
	s_cbranch_scc1 .Lg1n_797
	s_waitcnt lgkmcnt(3)
	v_mfma_f32_16x16x32_bf16 v[126:129], v[180:183], v[164:167], v[126:129]
	v_mfma_f32_16x16x32_bf16 v[110:113], v[180:183], v[168:171], v[110:113]
	v_mfma_f32_16x16x32_bf16 v[94:97], v[180:183], v[172:175], v[94:97]
	v_mfma_f32_16x16x32_bf16 v[78:81], v[180:183], v[176:179], v[78:81]
	s_add_i32 m0, s101, 0x4000
	ds_read_b128 v[240:243], v199
	ds_read_b128 v[244:247], v200
	global_load_lds_dwordx4 v144, s[98:99]
	s_waitcnt lgkmcnt(4)
	v_mfma_f32_16x16x32_bf16 v[122:125], v[184:187], v[164:167], v[122:125]
	v_mfma_f32_16x16x32_bf16 v[106:109], v[184:187], v[168:171], v[106:109]
	v_mfma_f32_16x16x32_bf16 v[90:93], v[184:187], v[172:175], v[90:93]
	v_mfma_f32_16x16x32_bf16 v[74:77], v[184:187], v[176:179], v[74:77]
	s_add_i32 m0, s101, 0xc000
	ds_read_b128 v[248:251], v201
	ds_read_b128 v[252:255], v202
	global_load_lds_dwordx4 v136, vcc
	s_waitcnt lgkmcnt(5)
	v_mfma_f32_16x16x32_bf16 v[118:121], v[188:191], v[164:167], v[118:121]
	v_mfma_f32_16x16x32_bf16 v[102:105], v[188:191], v[168:171], v[102:105]
	v_mfma_f32_16x16x32_bf16 v[86:89], v[188:191], v[172:175], v[86:89]
	s_add_i32 m0, s101, 0x6000
	v_mfma_f32_16x16x32_bf16 v[70:73], v[188:191], v[176:179], v[70:73]
	global_load_lds_dwordx4 v142, s[98:99]
	s_waitcnt lgkmcnt(4)
	v_mfma_f32_16x16x32_bf16 v[114:117], v[192:195], v[164:167], v[114:117]
	v_mfma_f32_16x16x32_bf16 v[98:101], v[192:195], v[168:171], v[98:101]
	v_mfma_f32_16x16x32_bf16 v[82:85], v[192:195], v[172:175], v[82:85]
	s_add_i32 m0, s101, 0xe000
	v_mfma_f32_16x16x32_bf16 v[66:69], v[192:195], v[176:179], v[66:69]
	global_load_lds_dwordx4 v134, vcc

.Lg2b_797:
	s_waitcnt lgkmcnt(3)
	v_mfma_f32_16x16x32_bf16 v[126:129], v[180:183], v[164:167], v[126:129]
	v_mfma_f32_16x16x32_bf16 v[110:113], v[180:183], v[168:171], v[110:113]
	v_mfma_f32_16x16x32_bf16 v[94:97], v[180:183], v[172:175], v[94:97]
	v_mfma_f32_16x16x32_bf16 v[78:81], v[180:183], v[176:179], v[78:81]
	ds_read_b128 v[240:243], v199 offset:1024
	ds_read_b128 v[244:247], v200 offset:1024
	s_waitcnt lgkmcnt(4)
	v_mfma_f32_16x16x32_bf16 v[122:125], v[184:187], v[164:167], v[122:125]
	v_mfma_f32_16x16x32_bf16 v[106:109], v[184:187], v[168:171], v[106:109]
	v_mfma_f32_16x16x32_bf16 v[90:93], v[184:187], v[172:175], v[90:93]
	v_mfma_f32_16x16x32_bf16 v[74:77], v[184:187], v[176:179], v[74:77]
	ds_read_b128 v[248:251], v201 offset:1024
	ds_read_b128 v[252:255], v202 offset:1024
	s_waitcnt lgkmcnt(5)
	v_mfma_f32_16x16x32_bf16 v[118:121], v[188:191], v[164:167], v[118:121]
	v_mfma_f32_16x16x32_bf16 v[102:105], v[188:191], v[168:171], v[102:105]
	v_mfma_f32_16x16x32_bf16 v[86:89], v[188:191], v[172:175], v[86:89]
	v_mfma_f32_16x16x32_bf16 v[70:73], v[188:191], v[176:179], v[70:73]
	s_waitcnt lgkmcnt(4)
	v_mfma_f32_16x16x32_bf16 v[114:117], v[192:195], v[164:167], v[114:117]
	v_mfma_f32_16x16x32_bf16 v[98:101], v[192:195], v[168:171], v[98:101]
	v_mfma_f32_16x16x32_bf16 v[82:85], v[192:195], v[172:175], v[82:85]
	v_mfma_f32_16x16x32_bf16 v[66:69], v[192:195], v[176:179], v[66:69]
	s_add_i32 s101, s100, s39
	s_cmpk_eq_i32 s36, 0x700
	s_cbranch_scc1 .Lg4n_797
	s_waitcnt vmcnt(0) lgkmcnt(0)
	s_barrier
	s_add_u32 s98, s98, 0x80
	s_addc_u32 s99, s99, 0
	s_add_u32 vcc_lo, vcc_lo, 0x80
	s_addc_u32 vcc_hi, vcc_hi, 0
	v_mfma_f32_16x16x32_bf16 v[62:65], v[180:183], v[240:243], v[62:65]
	v_mfma_f32_16x16x32_bf16 v[46:49], v[180:183], v[244:247], v[46:49]
	v_mfma_f32_16x16x32_bf16 v[18:21], v[180:183], v[248:251], v[18:21]
	v_mfma_f32_16x16x32_bf16 v[38:41], v[180:183], v[252:255], v[38:41]
	s_mov_b32 m0, s101
	v_add3_u32 v130, s42, v152, v153
	ds_read_b128 v[180:183], v130 offset:32768
	v_add3_u32 v163, s42, v152, v154
	v_add3_u32 v196, s42, v156, v155
	v_add3_u32 v197, s42, v156, v157
	v_add3_u32 v198, s42, v156, v158
	ds_read_b128 v[164:167], v163
	ds_read_b128 v[168:171], v196
	ds_read_b128 v[172:175], v197
	ds_read_b128 v[176:179], v198
	global_load_lds_dwordx4 v148, s[98:99]
	v_mfma_f32_16x16x32_bf16 v[58:61], v[184:187], v[240:243], v[58:61]
	v_mfma_f32_16x16x32_bf16 v[42:45], v[184:187], v[244:247], v[42:45]
	v_mfma_f32_16x16x32_bf16 v[14:17], v[184:187], v[248:251], v[14:17]
	v_mfma_f32_16x16x32_bf16 v[30:33], v[184:187], v[252:255], v[30:33]
	s_add_i32 m0, s101, 0x8000
	ds_read_b128 v[184:187], v130 offset:34816
	v_add3_u32 v199, s42, v156, v159
	v_add3_u32 v200, s42, v156, v160
	v_add3_u32 v201, s42, v156, v161
	v_add3_u32 v202, s42, v156, v162
	global_load_lds_dwordx4 v140, vcc
	v_mfma_f32_16x16x32_bf16 v[54:57], v[188:191], v[240:243], v[54:57]
	v_mfma_f32_16x16x32_bf16 v[34:37], v[188:191], v[244:247], v[34:37]
	v_mfma_f32_16x16x32_bf16 v[6:9], v[188:191], v[248:251], v[6:9]
	v_mfma_f32_16x16x32_bf16 v[22:25], v[188:191], v[252:255], v[22:25]
	s_add_i32 m0, s101, 0x2000
	ds_read_b128 v[188:191], v130 offset:36864
	global_load_lds_dwordx4 v146, s[98:99]
	v_mfma_f32_16x16x32_bf16 v[50:53], v[192:195], v[240:243], v[50:53]
	v_mfma_f32_16x16x32_bf16 v[26:29], v[192:195], v[244:247], v[26:29]
	v_mfma_f32_16x16x32_bf16 v[2:5], v[192:195], v[248:251], v[2:5]
	v_mfma_f32_16x16x32_bf16 v[10:13], v[192:195], v[252:255], v[10:13]
	s_add_i32 m0, s101, 0xa000
	ds_read_b128 v[192:195], v130 offset:38912
	global_load_lds_dwordx4 v138, vcc

.LBB0_846:
	s_and_b32 s29, s15, 0x10000
	s_xor_b32 s30, s29, 0x10000
	s_add_i32 s29, s29, 0
	s_add_i32 s101, s100, s30
	s_cmpk_eq_i32 s16, 0
	s_cbranch_scc1 .Lg1n_846
	s_waitcnt lgkmcnt(3)
	v_mfma_f32_16x16x32_bf16 v[124:127], v[178:181], v[162:165], v[124:127]
	v_mfma_f32_16x16x32_bf16 v[108:111], v[178:181], v[166:169], v[108:111]
	v_mfma_f32_16x16x32_bf16 v[92:95], v[178:181], v[170:173], v[92:95]
	v_mfma_f32_16x16x32_bf16 v[76:79], v[178:181], v[174:177], v[76:79]
	s_add_i32 m0, s101, 0x4000
	ds_read_b128 v[240:243], v197
	ds_read_b128 v[244:247], v198
	global_load_lds_dwordx4 v142, s[98:99]
	s_waitcnt lgkmcnt(4)
	v_mfma_f32_16x16x32_bf16 v[120:123], v[182:185], v[162:165], v[120:123]
	v_mfma_f32_16x16x32_bf16 v[104:107], v[182:185], v[166:169], v[104:107]
	v_mfma_f32_16x16x32_bf16 v[88:91], v[182:185], v[170:173], v[88:91]
	v_mfma_f32_16x16x32_bf16 v[72:75], v[182:185], v[174:177], v[72:75]
	s_add_i32 m0, s101, 0xc000
	ds_read_b128 v[248:251], v199
	ds_read_b128 v[252:255], v200
	global_load_lds_dwordx4 v134, vcc
	s_waitcnt lgkmcnt(5)
	v_mfma_f32_16x16x32_bf16 v[116:119], v[186:189], v[162:165], v[116:119]
	v_mfma_f32_16x16x32_bf16 v[100:103], v[186:189], v[166:169], v[100:103]
	v_mfma_f32_16x16x32_bf16 v[84:87], v[186:189], v[170:173], v[84:87]
	s_add_i32 m0, s101, 0x6000
	v_mfma_f32_16x16x32_bf16 v[68:71], v[186:189], v[174:177], v[68:71]
	global_load_lds_dwordx4 v140, s[98:99]
	s_waitcnt lgkmcnt(4)
	v_mfma_f32_16x16x32_bf16 v[112:115], v[190:193], v[162:165], v[112:115]
	v_mfma_f32_16x16x32_bf16 v[96:99], v[190:193], v[166:169], v[96:99]
	v_mfma_f32_16x16x32_bf16 v[80:83], v[190:193], v[170:173], v[80:83]
	s_add_i32 m0, s101, 0xe000
	v_mfma_f32_16x16x32_bf16 v[64:67], v[190:193], v[174:177], v[64:67]
	global_load_lds_dwordx4 v130, vcc

.Lg2b_846:
	s_waitcnt lgkmcnt(3)
	v_mfma_f32_16x16x32_bf16 v[124:127], v[178:181], v[162:165], v[124:127]
	v_mfma_f32_16x16x32_bf16 v[108:111], v[178:181], v[166:169], v[108:111]
	v_mfma_f32_16x16x32_bf16 v[92:95], v[178:181], v[170:173], v[92:95]
	v_mfma_f32_16x16x32_bf16 v[76:79], v[178:181], v[174:177], v[76:79]
	ds_read_b128 v[240:243], v197 offset:1024
	ds_read_b128 v[244:247], v198 offset:1024
	s_waitcnt lgkmcnt(4)
	v_mfma_f32_16x16x32_bf16 v[120:123], v[182:185], v[162:165], v[120:123]
	v_mfma_f32_16x16x32_bf16 v[104:107], v[182:185], v[166:169], v[104:107]
	v_mfma_f32_16x16x32_bf16 v[88:91], v[182:185], v[170:173], v[88:91]
	v_mfma_f32_16x16x32_bf16 v[72:75], v[182:185], v[174:177], v[72:75]
	ds_read_b128 v[248:251], v199 offset:1024
	ds_read_b128 v[252:255], v200 offset:1024
	s_waitcnt lgkmcnt(5)
	v_mfma_f32_16x16x32_bf16 v[116:119], v[186:189], v[162:165], v[116:119]
	v_mfma_f32_16x16x32_bf16 v[100:103], v[186:189], v[166:169], v[100:103]
	v_mfma_f32_16x16x32_bf16 v[84:87], v[186:189], v[170:173], v[84:87]
	v_mfma_f32_16x16x32_bf16 v[68:71], v[186:189], v[174:177], v[68:71]
	s_waitcnt lgkmcnt(4)
	v_mfma_f32_16x16x32_bf16 v[112:115], v[190:193], v[162:165], v[112:115]
	v_mfma_f32_16x16x32_bf16 v[96:99], v[190:193], v[166:169], v[96:99]
	v_mfma_f32_16x16x32_bf16 v[80:83], v[190:193], v[170:173], v[80:83]
	v_mfma_f32_16x16x32_bf16 v[64:67], v[190:193], v[174:177], v[64:67]
	s_add_i32 s101, s100, s29
	s_cmpk_eq_i32 s16, 0x700
	s_cbranch_scc1 .Lg4n_846
	s_waitcnt vmcnt(0) lgkmcnt(0)
	s_barrier
	s_add_u32 s98, s98, 0x80
	s_addc_u32 s99, s99, 0
	s_add_u32 vcc_lo, vcc_lo, 0x80
	s_addc_u32 vcc_hi, vcc_hi, 0
	v_mfma_f32_16x16x32_bf16 v[60:63], v[178:181], v[240:243], v[60:63]
	v_mfma_f32_16x16x32_bf16 v[44:47], v[178:181], v[244:247], v[44:47]
	v_mfma_f32_16x16x32_bf16 v[16:19], v[178:181], v[248:251], v[16:19]
	v_mfma_f32_16x16x32_bf16 v[36:39], v[178:181], v[252:255], v[36:39]
	s_mov_b32 m0, s101
	v_add3_u32 v128, s30, v150, v151
	ds_read_b128 v[178:181], v128 offset:32768
	v_add3_u32 v161, s30, v150, v152
	v_add3_u32 v194, s30, v154, v153
	v_add3_u32 v195, s30, v154, v155
	v_add3_u32 v196, s30, v154, v156
	ds_read_b128 v[162:165], v161
	ds_read_b128 v[166:169], v194
	ds_read_b128 v[170:173], v195
	ds_read_b128 v[174:177], v196
	global_load_lds_dwordx4 v146, s[98:99]
	v_mfma_f32_16x16x32_bf16 v[56:59], v[182:185], v[240:243], v[56:59]
	v_mfma_f32_16x16x32_bf16 v[40:43], v[182:185], v[244:247], v[40:43]
	v_mfma_f32_16x16x32_bf16 v[8:11], v[182:185], v[248:251], v[8:11]
	v_mfma_f32_16x16x32_bf16 v[28:31], v[182:185], v[252:255], v[28:31]
	s_add_i32 m0, s101, 0x8000
	ds_read_b128 v[182:185], v128 offset:34816
	v_add3_u32 v197, s30, v154, v157
	v_add3_u32 v198, s30, v154, v158
	v_add3_u32 v199, s30, v154, v159
	v_add3_u32 v200, s30, v154, v160
	global_load_lds_dwordx4 v138, vcc
	v_mfma_f32_16x16x32_bf16 v[52:55], v[186:189], v[240:243], v[52:55]
	v_mfma_f32_16x16x32_bf16 v[32:35], v[186:189], v[244:247], v[32:35]
	v_mfma_f32_16x16x32_bf16 v[4:7], v[186:189], v[248:251], v[4:7]
	v_mfma_f32_16x16x32_bf16 v[20:23], v[186:189], v[252:255], v[20:23]
	s_add_i32 m0, s101, 0x2000
	ds_read_b128 v[186:189], v128 offset:36864
	global_load_lds_dwordx4 v144, s[98:99]
	v_mfma_f32_16x16x32_bf16 v[48:51], v[190:193], v[240:243], v[48:51]
	v_mfma_f32_16x16x32_bf16 v[24:27], v[190:193], v[244:247], v[24:27]
	v_mfma_f32_16x16x32_bf16 v[0:3], v[190:193], v[248:251], v[0:3]
	v_mfma_f32_16x16x32_bf16 v[12:15], v[190:193], v[252:255], v[12:15]
	s_add_i32 m0, s101, 0xa000
	ds_read_b128 v[190:193], v128 offset:38912
	global_load_lds_dwordx4 v136, vcc

.LBB0_942:
	s_and_b32 s17, s15, 0x10000
	s_xor_b32 s42, s17, 0x10000
	s_add_i32 s17, s17, 0
	s_add_i32 s101, s100, s42
	s_cmpk_eq_i32 s18, 0
	s_cbranch_scc1 .Lg1n_942
	s_waitcnt lgkmcnt(3)
	v_mfma_f32_16x16x32_bf16 v[108:111], v[178:181], v[162:165], v[108:111]
	v_mfma_f32_16x16x32_bf16 v[92:95], v[178:181], v[166:169], v[92:95]
	v_mfma_f32_16x16x32_bf16 v[76:79], v[178:181], v[170:173], v[76:79]
	v_mfma_f32_16x16x32_bf16 v[60:63], v[178:181], v[174:177], v[60:63]
	s_add_i32 m0, s101, 0x4000
	ds_read_b128 v[240:243], v197
	ds_read_b128 v[244:247], v198
	global_load_lds_dwordx4 v142, s[98:99]
	s_waitcnt lgkmcnt(4)
	v_mfma_f32_16x16x32_bf16 v[104:107], v[182:185], v[162:165], v[104:107]
	v_mfma_f32_16x16x32_bf16 v[88:91], v[182:185], v[166:169], v[88:91]
	v_mfma_f32_16x16x32_bf16 v[72:75], v[182:185], v[170:173], v[72:75]
	v_mfma_f32_16x16x32_bf16 v[56:59], v[182:185], v[174:177], v[56:59]
	s_add_i32 m0, s101, 0xc000
	ds_read_b128 v[248:251], v199
	ds_read_b128 v[252:255], v200
	global_load_lds_dwordx4 v134, vcc
	s_waitcnt lgkmcnt(5)
	v_mfma_f32_16x16x32_bf16 v[100:103], v[186:189], v[162:165], v[100:103]
	v_mfma_f32_16x16x32_bf16 v[84:87], v[186:189], v[166:169], v[84:87]
	v_mfma_f32_16x16x32_bf16 v[68:71], v[186:189], v[170:173], v[68:71]
	s_add_i32 m0, s101, 0x6000
	v_mfma_f32_16x16x32_bf16 v[52:55], v[186:189], v[174:177], v[52:55]
	global_load_lds_dwordx4 v140, s[98:99]
	s_waitcnt lgkmcnt(4)
	v_mfma_f32_16x16x32_bf16 v[96:99], v[190:193], v[162:165], v[96:99]
	v_mfma_f32_16x16x32_bf16 v[80:83], v[190:193], v[166:169], v[80:83]
	v_mfma_f32_16x16x32_bf16 v[64:67], v[190:193], v[170:173], v[64:67]
	s_add_i32 m0, s101, 0xe000
	v_mfma_f32_16x16x32_bf16 v[48:51], v[190:193], v[174:177], v[48:51]
	global_load_lds_dwordx4 v130, vcc

.Lg2b_942:
	s_waitcnt lgkmcnt(3)
	v_mfma_f32_16x16x32_bf16 v[108:111], v[178:181], v[162:165], v[108:111]
	v_mfma_f32_16x16x32_bf16 v[92:95], v[178:181], v[166:169], v[92:95]
	v_mfma_f32_16x16x32_bf16 v[76:79], v[178:181], v[170:173], v[76:79]
	v_mfma_f32_16x16x32_bf16 v[60:63], v[178:181], v[174:177], v[60:63]
	ds_read_b128 v[240:243], v197 offset:1024
	ds_read_b128 v[244:247], v198 offset:1024
	s_waitcnt lgkmcnt(4)
	v_mfma_f32_16x16x32_bf16 v[104:107], v[182:185], v[162:165], v[104:107]
	v_mfma_f32_16x16x32_bf16 v[88:91], v[182:185], v[166:169], v[88:91]
	v_mfma_f32_16x16x32_bf16 v[72:75], v[182:185], v[170:173], v[72:75]
	v_mfma_f32_16x16x32_bf16 v[56:59], v[182:185], v[174:177], v[56:59]
	ds_read_b128 v[248:251], v199 offset:1024
	ds_read_b128 v[252:255], v200 offset:1024
	s_waitcnt lgkmcnt(5)
	v_mfma_f32_16x16x32_bf16 v[100:103], v[186:189], v[162:165], v[100:103]
	v_mfma_f32_16x16x32_bf16 v[84:87], v[186:189], v[166:169], v[84:87]
	v_mfma_f32_16x16x32_bf16 v[68:71], v[186:189], v[170:173], v[68:71]
	v_mfma_f32_16x16x32_bf16 v[52:55], v[186:189], v[174:177], v[52:55]
	s_waitcnt lgkmcnt(4)
	v_mfma_f32_16x16x32_bf16 v[96:99], v[190:193], v[162:165], v[96:99]
	v_mfma_f32_16x16x32_bf16 v[80:83], v[190:193], v[166:169], v[80:83]
	v_mfma_f32_16x16x32_bf16 v[64:67], v[190:193], v[170:173], v[64:67]
	v_mfma_f32_16x16x32_bf16 v[48:51], v[190:193], v[174:177], v[48:51]
	s_add_i32 s101, s100, s17
	s_cmpk_eq_i32 s18, 0x700
	s_cbranch_scc1 .Lg4n_942
	s_waitcnt vmcnt(0) lgkmcnt(0)
	s_barrier
	s_add_u32 s98, s98, 0x80
	s_addc_u32 s99, s99, 0
	s_add_u32 vcc_lo, vcc_lo, 0x80
	s_addc_u32 vcc_hi, vcc_hi, 0
	v_mfma_f32_16x16x32_bf16 v[44:47], v[178:181], v[240:243], v[44:47]
	v_mfma_f32_16x16x32_bf16 v[28:31], v[178:181], v[244:247], v[28:31]
	v_mfma_f32_16x16x32_bf16 v[12:15], v[178:181], v[248:251], v[12:15]
	v_mfma_f32_16x16x32_bf16 v[112:115], v[178:181], v[252:255], v[112:115]
	s_mov_b32 m0, s101
	v_add3_u32 v128, s42, v150, v151
	ds_read_b128 v[178:181], v128 offset:32768
	v_add3_u32 v161, s42, v150, v152
	v_add3_u32 v194, s42, v154, v153
	v_add3_u32 v195, s42, v154, v155
	v_add3_u32 v196, s42, v154, v156
	ds_read_b128 v[162:165], v161
	ds_read_b128 v[166:169], v194
	ds_read_b128 v[170:173], v195
	ds_read_b128 v[174:177], v196
	global_load_lds_dwordx4 v146, s[98:99]
	v_mfma_f32_16x16x32_bf16 v[40:43], v[182:185], v[240:243], v[40:43]
	v_mfma_f32_16x16x32_bf16 v[24:27], v[182:185], v[244:247], v[24:27]
	v_mfma_f32_16x16x32_bf16 v[8:11], v[182:185], v[248:251], v[8:11]
	v_mfma_f32_16x16x32_bf16 v[116:119], v[182:185], v[252:255], v[116:119]
	s_add_i32 m0, s101, 0x8000
	ds_read_b128 v[182:185], v128 offset:34816
	v_add3_u32 v197, s42, v154, v157
	v_add3_u32 v198, s42, v154, v158
	v_add3_u32 v199, s42, v154, v159
	v_add3_u32 v200, s42, v154, v160
	global_load_lds_dwordx4 v138, vcc
	v_mfma_f32_16x16x32_bf16 v[36:39], v[186:189], v[240:243], v[36:39]
	v_mfma_f32_16x16x32_bf16 v[20:23], v[186:189], v[244:247], v[20:23]
	v_mfma_f32_16x16x32_bf16 v[4:7], v[186:189], v[248:251], v[4:7]
	v_mfma_f32_16x16x32_bf16 v[120:123], v[186:189], v[252:255], v[120:123]
	s_add_i32 m0, s101, 0x2000
	ds_read_b128 v[186:189], v128 offset:36864
	global_load_lds_dwordx4 v144, s[98:99]
	v_mfma_f32_16x16x32_bf16 v[32:35], v[190:193], v[240:243], v[32:35]
	v_mfma_f32_16x16x32_bf16 v[16:19], v[190:193], v[244:247], v[16:19]
	v_mfma_f32_16x16x32_bf16 v[0:3], v[190:193], v[248:251], v[0:3]
	v_mfma_f32_16x16x32_bf16 v[124:127], v[190:193], v[252:255], v[124:127]
	s_add_i32 m0, s101, 0xa000
	ds_read_b128 v[190:193], v128 offset:38912
	global_load_lds_dwordx4 v136, vcc

.LBB0_1040:
	s_and_b32 s17, s15, 0x10000
	s_xor_b32 s43, s17, 0x10000
	s_add_i32 s17, s17, 0
	s_add_i32 s101, s100, s43
	s_cmpk_eq_i32 s18, 0
	s_cbranch_scc1 .Lg1n_1040
	s_waitcnt lgkmcnt(3)
	v_mfma_f32_16x16x32_bf16 v[108:111], v[178:181], v[162:165], v[108:111]
	v_mfma_f32_16x16x32_bf16 v[92:95], v[178:181], v[166:169], v[92:95]
	v_mfma_f32_16x16x32_bf16 v[76:79], v[178:181], v[170:173], v[76:79]
	v_mfma_f32_16x16x32_bf16 v[60:63], v[178:181], v[174:177], v[60:63]
	s_add_i32 m0, s101, 0x4000
	ds_read_b128 v[240:243], v197
	ds_read_b128 v[244:247], v198
	global_load_lds_dwordx4 v142, s[98:99]
	s_waitcnt lgkmcnt(4)
	v_mfma_f32_16x16x32_bf16 v[104:107], v[182:185], v[162:165], v[104:107]
	v_mfma_f32_16x16x32_bf16 v[88:91], v[182:185], v[166:169], v[88:91]
	v_mfma_f32_16x16x32_bf16 v[72:75], v[182:185], v[170:173], v[72:75]
	v_mfma_f32_16x16x32_bf16 v[56:59], v[182:185], v[174:177], v[56:59]
	s_add_i32 m0, s101, 0xc000
	ds_read_b128 v[248:251], v199
	ds_read_b128 v[252:255], v200
	global_load_lds_dwordx4 v134, vcc
	s_waitcnt lgkmcnt(5)
	v_mfma_f32_16x16x32_bf16 v[100:103], v[186:189], v[162:165], v[100:103]
	v_mfma_f32_16x16x32_bf16 v[84:87], v[186:189], v[166:169], v[84:87]
	v_mfma_f32_16x16x32_bf16 v[68:71], v[186:189], v[170:173], v[68:71]
	s_add_i32 m0, s101, 0x6000
	v_mfma_f32_16x16x32_bf16 v[52:55], v[186:189], v[174:177], v[52:55]
	global_load_lds_dwordx4 v140, s[98:99]
	s_waitcnt lgkmcnt(4)
	v_mfma_f32_16x16x32_bf16 v[96:99], v[190:193], v[162:165], v[96:99]
	v_mfma_f32_16x16x32_bf16 v[80:83], v[190:193], v[166:169], v[80:83]
	v_mfma_f32_16x16x32_bf16 v[64:67], v[190:193], v[170:173], v[64:67]
	s_add_i32 m0, s101, 0xe000
	v_mfma_f32_16x16x32_bf16 v[48:51], v[190:193], v[174:177], v[48:51]
	global_load_lds_dwordx4 v130, vcc

.Lg2b_1040:
	s_waitcnt lgkmcnt(3)
	v_mfma_f32_16x16x32_bf16 v[108:111], v[178:181], v[162:165], v[108:111]
	v_mfma_f32_16x16x32_bf16 v[92:95], v[178:181], v[166:169], v[92:95]
	v_mfma_f32_16x16x32_bf16 v[76:79], v[178:181], v[170:173], v[76:79]
	v_mfma_f32_16x16x32_bf16 v[60:63], v[178:181], v[174:177], v[60:63]
	ds_read_b128 v[240:243], v197 offset:1024
	ds_read_b128 v[244:247], v198 offset:1024
	s_waitcnt lgkmcnt(4)
	v_mfma_f32_16x16x32_bf16 v[104:107], v[182:185], v[162:165], v[104:107]
	v_mfma_f32_16x16x32_bf16 v[88:91], v[182:185], v[166:169], v[88:91]
	v_mfma_f32_16x16x32_bf16 v[72:75], v[182:185], v[170:173], v[72:75]
	v_mfma_f32_16x16x32_bf16 v[56:59], v[182:185], v[174:177], v[56:59]
	ds_read_b128 v[248:251], v199 offset:1024
	ds_read_b128 v[252:255], v200 offset:1024
	s_waitcnt lgkmcnt(5)
	v_mfma_f32_16x16x32_bf16 v[100:103], v[186:189], v[162:165], v[100:103]
	v_mfma_f32_16x16x32_bf16 v[84:87], v[186:189], v[166:169], v[84:87]
	v_mfma_f32_16x16x32_bf16 v[68:71], v[186:189], v[170:173], v[68:71]
	v_mfma_f32_16x16x32_bf16 v[52:55], v[186:189], v[174:177], v[52:55]
	s_waitcnt lgkmcnt(4)
	v_mfma_f32_16x16x32_bf16 v[96:99], v[190:193], v[162:165], v[96:99]
	v_mfma_f32_16x16x32_bf16 v[80:83], v[190:193], v[166:169], v[80:83]
	v_mfma_f32_16x16x32_bf16 v[64:67], v[190:193], v[170:173], v[64:67]
	v_mfma_f32_16x16x32_bf16 v[48:51], v[190:193], v[174:177], v[48:51]
	s_add_i32 s101, s100, s17
	s_cmpk_eq_i32 s18, 0x700
	s_cbranch_scc1 .Lg4n_1040
	s_waitcnt vmcnt(0) lgkmcnt(0)
	s_barrier
	s_add_u32 s98, s98, 0x80
	s_addc_u32 s99, s99, 0
	s_add_u32 vcc_lo, vcc_lo, 0x80
	s_addc_u32 vcc_hi, vcc_hi, 0
	v_mfma_f32_16x16x32_bf16 v[44:47], v[178:181], v[240:243], v[44:47]
	v_mfma_f32_16x16x32_bf16 v[28:31], v[178:181], v[244:247], v[28:31]
	v_mfma_f32_16x16x32_bf16 v[12:15], v[178:181], v[248:251], v[12:15]
	v_mfma_f32_16x16x32_bf16 v[112:115], v[178:181], v[252:255], v[112:115]
	s_mov_b32 m0, s101
	v_add3_u32 v128, s43, v150, v151
	ds_read_b128 v[178:181], v128 offset:32768
	v_add3_u32 v161, s43, v150, v152
	v_add3_u32 v194, s43, v154, v153
	v_add3_u32 v195, s43, v154, v155
	v_add3_u32 v196, s43, v154, v156
	ds_read_b128 v[162:165], v161
	ds_read_b128 v[166:169], v194
	ds_read_b128 v[170:173], v195
	ds_read_b128 v[174:177], v196
	global_load_lds_dwordx4 v146, s[98:99]
	v_mfma_f32_16x16x32_bf16 v[40:43], v[182:185], v[240:243], v[40:43]
	v_mfma_f32_16x16x32_bf16 v[24:27], v[182:185], v[244:247], v[24:27]
	v_mfma_f32_16x16x32_bf16 v[8:11], v[182:185], v[248:251], v[8:11]
	v_mfma_f32_16x16x32_bf16 v[116:119], v[182:185], v[252:255], v[116:119]
	s_add_i32 m0, s101, 0x8000
	ds_read_b128 v[182:185], v128 offset:34816
	v_add3_u32 v197, s43, v154, v157
	v_add3_u32 v198, s43, v154, v158
	v_add3_u32 v199, s43, v154, v159
	v_add3_u32 v200, s43, v154, v160
	global_load_lds_dwordx4 v138, vcc
	v_mfma_f32_16x16x32_bf16 v[36:39], v[186:189], v[240:243], v[36:39]
	v_mfma_f32_16x16x32_bf16 v[20:23], v[186:189], v[244:247], v[20:23]
	v_mfma_f32_16x16x32_bf16 v[4:7], v[186:189], v[248:251], v[4:7]
	v_mfma_f32_16x16x32_bf16 v[120:123], v[186:189], v[252:255], v[120:123]
	s_add_i32 m0, s101, 0x2000
	ds_read_b128 v[186:189], v128 offset:36864
	global_load_lds_dwordx4 v144, s[98:99]
	v_mfma_f32_16x16x32_bf16 v[32:35], v[190:193], v[240:243], v[32:35]
	v_mfma_f32_16x16x32_bf16 v[16:19], v[190:193], v[244:247], v[16:19]
	v_mfma_f32_16x16x32_bf16 v[0:3], v[190:193], v[248:251], v[0:3]
	v_mfma_f32_16x16x32_bf16 v[124:127], v[190:193], v[252:255], v[124:127]
	s_add_i32 m0, s101, 0xa000
	ds_read_b128 v[190:193], v128 offset:38912
	global_load_lds_dwordx4 v136, vcc

.LBB0_1138:
	s_and_b32 s27, s26, 0x10000
	s_xor_b32 s28, s27, 0x10000
	s_add_i32 s27, s27, 0
	s_add_i32 s101, s100, s28
	s_cmpk_eq_i32 s12, 0
	s_cbranch_scc1 .Lg1n_1138
	s_waitcnt lgkmcnt(3)
	v_mfma_f32_16x16x32_bf16 v[124:127], v[178:181], v[162:165], v[124:127]
	v_mfma_f32_16x16x32_bf16 v[108:111], v[178:181], v[166:169], v[108:111]
	v_mfma_f32_16x16x32_bf16 v[92:95], v[178:181], v[170:173], v[92:95]
	v_mfma_f32_16x16x32_bf16 v[76:79], v[178:181], v[174:177], v[76:79]
	s_add_i32 m0, s101, 0x4000
	ds_read_b128 v[240:243], v197
	ds_read_b128 v[244:247], v198
	global_load_lds_dwordx4 v142, s[98:99]
	s_waitcnt lgkmcnt(4)
	v_mfma_f32_16x16x32_bf16 v[120:123], v[182:185], v[162:165], v[120:123]
	v_mfma_f32_16x16x32_bf16 v[104:107], v[182:185], v[166:169], v[104:107]
	v_mfma_f32_16x16x32_bf16 v[88:91], v[182:185], v[170:173], v[88:91]
	v_mfma_f32_16x16x32_bf16 v[72:75], v[182:185], v[174:177], v[72:75]
	s_add_i32 m0, s101, 0xc000
	ds_read_b128 v[248:251], v199
	ds_read_b128 v[252:255], v200
	global_load_lds_dwordx4 v134, vcc
	s_waitcnt lgkmcnt(5)
	v_mfma_f32_16x16x32_bf16 v[116:119], v[186:189], v[162:165], v[116:119]
	v_mfma_f32_16x16x32_bf16 v[100:103], v[186:189], v[166:169], v[100:103]
	v_mfma_f32_16x16x32_bf16 v[84:87], v[186:189], v[170:173], v[84:87]
	s_add_i32 m0, s101, 0x6000
	v_mfma_f32_16x16x32_bf16 v[68:71], v[186:189], v[174:177], v[68:71]
	global_load_lds_dwordx4 v140, s[98:99]
	s_waitcnt lgkmcnt(4)
	v_mfma_f32_16x16x32_bf16 v[112:115], v[190:193], v[162:165], v[112:115]
	v_mfma_f32_16x16x32_bf16 v[96:99], v[190:193], v[166:169], v[96:99]
	v_mfma_f32_16x16x32_bf16 v[80:83], v[190:193], v[170:173], v[80:83]
	s_add_i32 m0, s101, 0xe000
	v_mfma_f32_16x16x32_bf16 v[64:67], v[190:193], v[174:177], v[64:67]
	global_load_lds_dwordx4 v130, vcc

.Lg2b_1138:
	s_waitcnt lgkmcnt(3)
	v_mfma_f32_16x16x32_bf16 v[124:127], v[178:181], v[162:165], v[124:127]
	v_mfma_f32_16x16x32_bf16 v[108:111], v[178:181], v[166:169], v[108:111]
	v_mfma_f32_16x16x32_bf16 v[92:95], v[178:181], v[170:173], v[92:95]
	v_mfma_f32_16x16x32_bf16 v[76:79], v[178:181], v[174:177], v[76:79]
	ds_read_b128 v[240:243], v197 offset:1024
	ds_read_b128 v[244:247], v198 offset:1024
	s_waitcnt lgkmcnt(4)
	v_mfma_f32_16x16x32_bf16 v[120:123], v[182:185], v[162:165], v[120:123]
	v_mfma_f32_16x16x32_bf16 v[104:107], v[182:185], v[166:169], v[104:107]
	v_mfma_f32_16x16x32_bf16 v[88:91], v[182:185], v[170:173], v[88:91]
	v_mfma_f32_16x16x32_bf16 v[72:75], v[182:185], v[174:177], v[72:75]
	ds_read_b128 v[248:251], v199 offset:1024
	ds_read_b128 v[252:255], v200 offset:1024
	s_waitcnt lgkmcnt(5)
	v_mfma_f32_16x16x32_bf16 v[116:119], v[186:189], v[162:165], v[116:119]
	v_mfma_f32_16x16x32_bf16 v[100:103], v[186:189], v[166:169], v[100:103]
	v_mfma_f32_16x16x32_bf16 v[84:87], v[186:189], v[170:173], v[84:87]
	v_mfma_f32_16x16x32_bf16 v[68:71], v[186:189], v[174:177], v[68:71]
	s_waitcnt lgkmcnt(4)
	v_mfma_f32_16x16x32_bf16 v[112:115], v[190:193], v[162:165], v[112:115]
	v_mfma_f32_16x16x32_bf16 v[96:99], v[190:193], v[166:169], v[96:99]
	v_mfma_f32_16x16x32_bf16 v[80:83], v[190:193], v[170:173], v[80:83]
	v_mfma_f32_16x16x32_bf16 v[64:67], v[190:193], v[174:177], v[64:67]
	s_add_i32 s101, s100, s27
	s_cmpk_eq_i32 s12, 0x1500
	s_cbranch_scc1 .Lg4n_1138
	s_waitcnt vmcnt(0) lgkmcnt(0)
	s_barrier
	s_add_u32 s98, s98, 0x80
	s_addc_u32 s99, s99, 0
	s_add_u32 vcc_lo, vcc_lo, 0x80
	s_addc_u32 vcc_hi, vcc_hi, 0
	v_mfma_f32_16x16x32_bf16 v[60:63], v[178:181], v[240:243], v[60:63]
	v_mfma_f32_16x16x32_bf16 v[44:47], v[178:181], v[244:247], v[44:47]
	v_mfma_f32_16x16x32_bf16 v[16:19], v[178:181], v[248:251], v[16:19]
	v_mfma_f32_16x16x32_bf16 v[36:39], v[178:181], v[252:255], v[36:39]
	s_mov_b32 m0, s101
	v_add3_u32 v128, s28, v150, v151
	ds_read_b128 v[178:181], v128 offset:32768
	v_add3_u32 v161, s28, v150, v152
	v_add3_u32 v194, s28, v154, v153
	v_add3_u32 v195, s28, v154, v155
	v_add3_u32 v196, s28, v154, v156
	ds_read_b128 v[162:165], v161
	ds_read_b128 v[166:169], v194
	ds_read_b128 v[170:173], v195
	ds_read_b128 v[174:177], v196
	global_load_lds_dwordx4 v146, s[98:99]
	v_mfma_f32_16x16x32_bf16 v[56:59], v[182:185], v[240:243], v[56:59]
	v_mfma_f32_16x16x32_bf16 v[40:43], v[182:185], v[244:247], v[40:43]
	v_mfma_f32_16x16x32_bf16 v[8:11], v[182:185], v[248:251], v[8:11]
	v_mfma_f32_16x16x32_bf16 v[28:31], v[182:185], v[252:255], v[28:31]
	s_add_i32 m0, s101, 0x8000
	ds_read_b128 v[182:185], v128 offset:34816
	v_add3_u32 v197, s28, v154, v157
	v_add3_u32 v198, s28, v154, v158
	v_add3_u32 v199, s28, v154, v159
	v_add3_u32 v200, s28, v154, v160
	global_load_lds_dwordx4 v138, vcc
	v_mfma_f32_16x16x32_bf16 v[52:55], v[186:189], v[240:243], v[52:55]
	v_mfma_f32_16x16x32_bf16 v[32:35], v[186:189], v[244:247], v[32:35]
	v_mfma_f32_16x16x32_bf16 v[4:7], v[186:189], v[248:251], v[4:7]
	v_mfma_f32_16x16x32_bf16 v[20:23], v[186:189], v[252:255], v[20:23]
	s_add_i32 m0, s101, 0x2000
	ds_read_b128 v[186:189], v128 offset:36864
	global_load_lds_dwordx4 v144, s[98:99]
	v_mfma_f32_16x16x32_bf16 v[48:51], v[190:193], v[240:243], v[48:51]
	v_mfma_f32_16x16x32_bf16 v[24:27], v[190:193], v[244:247], v[24:27]
	v_mfma_f32_16x16x32_bf16 v[0:3], v[190:193], v[248:251], v[0:3]
	v_mfma_f32_16x16x32_bf16 v[12:15], v[190:193], v[252:255], v[12:15]
	s_add_i32 m0, s101, 0xa000
	ds_read_b128 v[190:193], v128 offset:38912
	global_load_lds_dwordx4 v136, vcc
